# combo5 + NSA block-selection arg-max shuffles via DPP moves instead of ds_bpermute (48 LDS round trips per unit removed)
# baseline (speedup 1.0000x reference)
.LBB0_898:
	v_cmp_lg_f32_e32 vcc, s85, v38
	s_nop 1
	v_cndmask_b32_e32 v48, v220, v38, vcc
	v_cndmask_b32_e32 v49, v225, v36, vcc
	v_cmp_gt_f32_e32 vcc, v37, v48
	s_nop 1
	v_cndmask_b32_e32 v48, v48, v37, vcc
	v_cndmask_b32_e32 v49, v49, v39, vcc
	v_cmp_gt_f32_e32 vcc, v42, v48
	s_nop 1
	v_cndmask_b32_e32 v48, v48, v42, vcc
	s_waitcnt lgkmcnt(0)
	v_cndmask_b32_e32 v51, v49, v40, vcc
	v_cmp_gt_f32_e32 vcc, v41, v48
	s_nop 1
	v_cndmask_b32_e32 v49, v48, v41, vcc
	s_nop 1
	v_mov_b32_dpp v50, v49 quad_perm:[1,0,3,2] row_mask:0xf bank_mask:0xf
	v_cndmask_b32_e32 v48, v51, v43, vcc
	s_nop 1
	v_mov_b32_dpp v51, v48 quad_perm:[1,0,3,2] row_mask:0xf bank_mask:0xf
	s_waitcnt lgkmcnt(1)
	v_cmp_lt_f32_e64 s[2:3], v49, v50
	v_cmp_nlt_f32_e32 vcc, v49, v50
	s_and_saveexec_b64 s[22:23], vcc
	s_cbranch_execz .LBB0_900
	v_cmp_eq_f32_e32 vcc, v49, v50
	s_waitcnt lgkmcnt(0)
	v_cmp_lt_i32_e64 s[38:39], v51, v48
	s_and_b64 s[38:39], vcc, s[38:39]
	s_andn2_b64 s[2:3], s[2:3], exec
	s_and_b64 s[38:39], s[38:39], exec
	s_or_b64 s[2:3], s[2:3], s[38:39]

.LBB0_902:
	s_or_b64 exec, exec, s[22:23]
	s_waitcnt lgkmcnt(0)
	s_nop 1
	v_mov_b32_dpp v51, v49 quad_perm:[2,3,0,1] row_mask:0xf bank_mask:0xf
	s_nop 1
	v_mov_b32_dpp v50, v48 quad_perm:[2,3,0,1] row_mask:0xf bank_mask:0xf
	s_waitcnt lgkmcnt(1)
	v_cmp_lt_f32_e64 s[2:3], v49, v51
	v_cmp_nlt_f32_e32 vcc, v49, v51
	s_and_saveexec_b64 s[22:23], vcc
	s_cbranch_execz .LBB0_904
	v_cmp_eq_f32_e32 vcc, v49, v51
	s_waitcnt lgkmcnt(0)
	v_cmp_lt_i32_e64 s[38:39], v50, v48
	s_and_b64 s[38:39], vcc, s[38:39]
	s_andn2_b64 s[2:3], s[2:3], exec
	s_and_b64 s[38:39], s[38:39], exec
	s_or_b64 s[2:3], s[2:3], s[38:39]

.LBB0_906:
	s_or_b64 exec, exec, s[22:23]
	s_waitcnt lgkmcnt(0)
	s_nop 1
	v_mov_b32_dpp v50, v49 row_half_mirror row_mask:0xf bank_mask:0xf
	s_nop 1
	v_mov_b32_dpp v51, v48 row_half_mirror row_mask:0xf bank_mask:0xf
	s_waitcnt lgkmcnt(1)
	v_cmp_lt_f32_e64 s[2:3], v49, v50
	v_cmp_nlt_f32_e32 vcc, v49, v50
	s_and_saveexec_b64 s[22:23], vcc
	s_cbranch_execz .LBB0_909
	v_cmp_eq_f32_e32 vcc, v49, v50
	s_waitcnt lgkmcnt(0)
	v_cmp_lt_i32_e64 s[38:39], v51, v48
	s_and_b64 s[38:39], vcc, s[38:39]
	s_andn2_b64 s[2:3], s[2:3], exec
	s_and_b64 s[38:39], s[38:39], exec
	s_or_b64 s[2:3], s[2:3], s[38:39]
	s_or_b64 exec, exec, s[22:23]
	s_and_saveexec_b64 s[22:23], s[2:3]
	s_cbranch_execnz .LBB0_910
